# final candidate plus nt hints on LN1 row loads, LN1 fp8 stores and KT row loads
# speedup vs baseline: 1.0066x; 1.0026x over previous
.LBB0_382:
	s_and_b32 s0, s2, 31
	s_and_b32 s6, s8, 0xffffffc0
	s_and_b32 s10, s2, 28
	s_getpc_b64 s[4:5]
	s_add_u32 s4, s4, _ZL5LOG2G@rel32@lo+4
	s_addc_u32 s5, s5, _ZL5LOG2G@rel32@hi+12
	s_and_b32 s7, s8, 64
	v_add_u32_e32 v30, s6, v4
	s_lshl_b32 s11, s0, 6
	s_lshl_b32 s0, s0, 7
	v_add_u32_e32 v32, s6, v8
	v_add_u32_e32 v34, s6, v9
	v_add_u32_e32 v36, s6, v10
	v_add_u32_e32 v38, s6, v11
	v_add_u32_e32 v40, s6, v12
	v_add_u32_e32 v42, s6, v13
	v_add_u32_e32 v44, s6, v6
	v_or_b32_e32 v48, s7, v5
	v_bitop3_b32 v49, s7, v29, v5 bitop3:0x36
	v_ashrrev_i32_e32 v31, 31, v30
	v_lshl_add_u64 v[46:47], v[0:1], 0, s[0:1]
	v_ashrrev_i32_e32 v33, 31, v32
	v_ashrrev_i32_e32 v35, 31, v34
	v_ashrrev_i32_e32 v37, 31, v36
	v_ashrrev_i32_e32 v39, 31, v38
	v_ashrrev_i32_e32 v41, 31, v40
	v_ashrrev_i32_e32 v43, 31, v42
	v_ashrrev_i32_e32 v45, 31, v44
	v_cvt_f32_ubyte0_e32 v94, v49
	v_sub_u32_e32 v49, 0x7e, v48
	v_sub_u32_e32 v51, 0x7d, v48
	v_sub_u32_e32 v53, 0x7c, v48
	v_sub_u32_e32 v55, 0x7b, v48
	v_sub_u32_e32 v57, 0x7a, v48
	v_sub_u32_e32 v59, 0x79, v48
	v_sub_u32_e32 v61, 0x78, v48
	v_add_u32_e32 v48, s11, v4
	v_add_u32_e32 v50, s11, v8
	v_add_u32_e32 v52, s11, v9
	v_add_u32_e32 v54, s11, v10
	v_add_u32_e32 v56, s11, v11
	v_add_u32_e32 v58, s11, v12
	v_add_u32_e32 v60, s11, v13
	v_lshlrev_b64 v[30:31], 12, v[30:31]
	v_lshlrev_b64 v[32:33], 12, v[32:33]
	v_lshlrev_b64 v[34:35], 12, v[34:35]
	v_lshlrev_b64 v[36:37], 12, v[36:37]
	v_lshlrev_b64 v[38:39], 12, v[38:39]
	v_lshlrev_b64 v[40:41], 12, v[40:41]
	v_lshlrev_b64 v[42:43], 12, v[42:43]
	v_lshlrev_b64 v[44:45], 12, v[44:45]
	v_cvt_f32_ubyte0_e32 v95, v49
	v_cvt_f32_ubyte0_e32 v96, v51
	v_cvt_f32_ubyte0_e32 v97, v53
	v_cvt_f32_ubyte0_e32 v98, v55
	v_cvt_f32_ubyte0_e32 v99, v57
	v_cvt_f32_ubyte0_e32 v100, v59
	v_cvt_f32_ubyte0_e32 v101, v61
	v_ashrrev_i32_e32 v49, 31, v48
	v_ashrrev_i32_e32 v51, 31, v50
	v_ashrrev_i32_e32 v53, 31, v52
	v_ashrrev_i32_e32 v55, 31, v54
	v_ashrrev_i32_e32 v57, 31, v56
	v_ashrrev_i32_e32 v59, 31, v58
	v_ashrrev_i32_e32 v61, 31, v60
	v_lshl_add_u64 v[30:31], v[46:47], 0, v[30:31]
	v_lshl_add_u64 v[66:67], v[46:47], 0, v[32:33]
	v_lshl_add_u64 v[68:69], v[46:47], 0, v[34:35]
	v_lshl_add_u64 v[70:71], v[46:47], 0, v[36:37]
	v_lshl_add_u64 v[72:73], v[46:47], 0, v[38:39]
	v_lshl_add_u64 v[74:75], v[46:47], 0, v[40:41]
	v_lshl_add_u64 v[76:77], v[46:47], 0, v[42:43]
	v_lshl_add_u64 v[78:79], v[46:47], 0, v[44:45]
	v_lshlrev_b64 v[80:81], 15, v[48:49]
	v_lshlrev_b64 v[82:83], 15, v[50:51]
	v_lshlrev_b64 v[84:85], 15, v[52:53]
	v_lshlrev_b64 v[86:87], 15, v[54:55]
	v_lshlrev_b64 v[88:89], 15, v[56:57]
	v_lshlrev_b64 v[90:91], 15, v[58:59]
	v_lshlrev_b64 v[92:93], 15, v[60:61]
	global_load_dwordx4 v[30:33], v[30:31], off nt
	s_nop 0
	global_load_dwordx4 v[34:37], v[66:67], off nt
	global_load_dwordx4 v[38:41], v[68:69], off nt
	global_load_dwordx4 v[42:45], v[70:71], off nt
	global_load_dwordx4 v[46:49], v[72:73], off nt
	global_load_dwordx4 v[50:53], v[74:75], off nt
	global_load_dwordx4 v[54:57], v[76:77], off nt
	global_load_dwordx4 v[58:61], v[78:79], off nt
	v_add_u32_e32 v64, s11, v6
	s_ashr_i32 s7, s6, 31
	v_ashrrev_i32_e32 v65, 31, v64
	v_lshl_add_u64 v[62:63], s[6:7], 1, v[2:3]
	v_lshlrev_b64 v[64:65], 15, v[64:65]
	v_lshl_add_u64 v[66:67], v[62:63], 0, v[80:81]
	v_lshl_add_u64 v[68:69], v[62:63], 0, v[82:83]
	s_waitcnt vmcnt(7)
	ds_write2_b32 v14, v30, v31 offset1:1
	ds_write2_b32 v14, v32, v33 offset0:2 offset1:3
	s_waitcnt vmcnt(6)
	ds_write2_b32 v15, v34, v35 offset1:1
	ds_write2_b32 v16, v36, v37 offset1:1
	s_waitcnt vmcnt(5)
	ds_write2_b32 v17, v38, v39 offset1:1
	ds_write2_b32 v18, v40, v41 offset1:1
	s_waitcnt vmcnt(4)
	ds_write2_b32 v19, v42, v43 offset1:1
	ds_write2_b32 v20, v44, v45 offset1:1
	s_waitcnt vmcnt(3)
	ds_write2_b32 v21, v46, v47 offset1:1
	ds_write2_b32 v22, v48, v49 offset1:1
	s_waitcnt vmcnt(2)
	ds_write2_b32 v23, v50, v51 offset1:1
	ds_write2_b32 v24, v52, v53 offset1:1
	s_waitcnt vmcnt(1)
	ds_write2_b32 v25, v54, v55 offset1:1
	ds_write2_b32 v26, v56, v57 offset1:1
	s_waitcnt vmcnt(0)
	ds_write2_b32 v27, v58, v59 offset1:1
	ds_write2_b32 v28, v60, v61 offset1:1
	s_waitcnt lgkmcnt(0)
	s_load_dword s0, s[4:5], s10 offset:0x0
	v_lshl_add_u64 v[70:71], v[62:63], 0, v[84:85]
	v_lshl_add_u64 v[72:73], v[62:63], 0, v[86:87]
	v_lshl_add_u64 v[74:75], v[62:63], 0, v[88:89]
	v_lshl_add_u64 v[76:77], v[62:63], 0, v[90:91]
	v_lshl_add_u64 v[78:79], v[62:63], 0, v[92:93]
	v_lshl_add_u64 v[62:63], v[62:63], 0, v[64:65]
	ds_read_u16 v30, v7
	ds_read_u16 v38, v7 offset:16
	ds_read_u16 v46, v7 offset:32
	ds_read_u16 v54, v7 offset:48
	ds_read_u16 v64, v7 offset:64
	ds_read_u16 v86, v7 offset:80
	ds_read_u16 v102, v7 offset:96
	ds_read_u16 v104, v7 offset:112
	ds_read_u16 v31, v7 offset:132
	ds_read_u16 v39, v7 offset:148
	ds_read_u16 v47, v7 offset:164
	ds_read_u16 v55, v7 offset:180
	ds_read_u16 v65, v7 offset:196
	ds_read_u16 v87, v7 offset:212
	ds_read_u16 v103, v7 offset:228
	ds_read_u16 v105, v7 offset:244
	ds_read_u16 v32, v7 offset:264
	ds_read_u16 v40, v7 offset:280
	ds_read_u16 v48, v7 offset:296
	ds_read_u16 v56, v7 offset:312
	ds_read_u16 v80, v7 offset:328
	ds_read_u16 v88, v7 offset:344
	ds_read_u16 v106, v7 offset:360
	ds_read_u16 v107, v7 offset:376
	ds_read_u16 v33, v7 offset:396
	ds_read_u16 v41, v7 offset:412
	ds_read_u16 v49, v7 offset:428
	ds_read_u16 v57, v7 offset:444
	ds_read_u16 v81, v7 offset:460
	ds_read_u16 v89, v7 offset:476
	ds_read_u16 v108, v7 offset:492
	ds_read_u16 v109, v7 offset:508
	ds_read_u16 v34, v7 offset:528
	ds_read_u16 v42, v7 offset:544
	ds_read_u16 v50, v7 offset:560
	ds_read_u16 v58, v7 offset:576
	ds_read_u16 v82, v7 offset:592
	ds_read_u16 v90, v7 offset:608
	ds_read_u16 v110, v7 offset:624
	ds_read_u16 v111, v7 offset:640
	ds_read_u16 v35, v7 offset:660
	ds_read_u16 v43, v7 offset:676
	ds_read_u16 v51, v7 offset:692
	ds_read_u16 v59, v7 offset:708
	ds_read_u16 v83, v7 offset:724
	ds_read_u16 v91, v7 offset:740
	ds_read_u16 v112, v7 offset:756
	ds_read_u16 v113, v7 offset:772
	ds_read_u16 v36, v7 offset:792
	ds_read_u16 v44, v7 offset:808
	ds_read_u16 v52, v7 offset:824
	ds_read_u16 v60, v7 offset:840
	ds_read_u16 v84, v7 offset:856
	ds_read_u16 v92, v7 offset:872
	ds_read_u16 v114, v7 offset:888
	ds_read_u16 v115, v7 offset:904
	ds_read_u16 v37, v7 offset:924
	ds_read_u16 v45, v7 offset:940
	ds_read_u16 v53, v7 offset:956
	ds_read_u16 v61, v7 offset:972
	ds_read_u16 v85, v7 offset:988
	ds_read_u16 v93, v7 offset:1004
	ds_read_u16 v116, v7 offset:1020
	ds_read_u16 v117, v7 offset:1036
	s_waitcnt lgkmcnt(0)
	v_mul_f32_e32 v118, s0, v94
	v_mul_f32_e32 v119, s0, v95
	v_mul_f32_e32 v120, s0, v96
	v_mul_f32_e32 v121, s0, v97
	v_mul_f32_e32 v122, s0, v98
	v_mul_f32_e32 v123, s0, v99
	v_mul_f32_e32 v124, s0, v100
	v_mul_f32_e32 v125, s0, v101
	v_lshlrev_b32_e32 v95, 16, v103
	v_lshlrev_b32_e32 v94, 16, v102
	v_lshlrev_b32_e32 v97, 16, v108
	v_lshlrev_b32_e32 v96, 16, v106
	v_lshlrev_b32_e32 v99, 16, v112
	v_lshlrev_b32_e32 v98, 16, v110
	v_lshlrev_b32_e32 v101, 16, v116
	v_lshlrev_b32_e32 v100, 16, v114
	v_lshlrev_b32_e32 v103, 16, v105
	v_lshlrev_b32_e32 v102, 16, v104
	v_lshlrev_b32_e32 v105, 16, v109
	v_lshlrev_b32_e32 v104, 16, v107
	v_lshlrev_b32_e32 v107, 16, v113
	v_lshlrev_b32_e32 v106, 16, v111
	v_lshlrev_b32_e32 v109, 16, v117
	v_lshlrev_b32_e32 v108, 16, v115
	v_exp_f32_e32 v110, v118
	v_exp_f32_e32 v111, v119
	v_exp_f32_e32 v112, v120
	v_exp_f32_e32 v113, v121
	v_exp_f32_e32 v114, v122
	v_exp_f32_e32 v115, v123
	v_exp_f32_e32 v116, v124
	v_exp_f32_e32 v117, v125
	v_lshlrev_b32_e32 v31, 16, v31
	v_lshlrev_b32_e32 v30, 16, v30
	v_lshlrev_b32_e32 v33, 16, v33
	v_lshlrev_b32_e32 v32, 16, v32
	v_lshlrev_b32_e32 v35, 16, v35
	v_lshlrev_b32_e32 v34, 16, v34
	v_lshlrev_b32_e32 v37, 16, v37
	v_lshlrev_b32_e32 v36, 16, v36
	v_lshlrev_b32_e32 v39, 16, v39
	v_lshlrev_b32_e32 v38, 16, v38
	v_lshlrev_b32_e32 v41, 16, v41
	v_lshlrev_b32_e32 v40, 16, v40
	v_lshlrev_b32_e32 v43, 16, v43
	v_lshlrev_b32_e32 v42, 16, v42
	v_lshlrev_b32_e32 v45, 16, v45
	v_lshlrev_b32_e32 v44, 16, v44
	v_lshlrev_b32_e32 v47, 16, v47
	v_lshlrev_b32_e32 v46, 16, v46
	v_lshlrev_b32_e32 v49, 16, v49
	v_lshlrev_b32_e32 v48, 16, v48
	v_lshlrev_b32_e32 v51, 16, v51
	v_lshlrev_b32_e32 v50, 16, v50
	v_lshlrev_b32_e32 v53, 16, v53
	v_lshlrev_b32_e32 v52, 16, v52
	v_lshlrev_b32_e32 v55, 16, v55
	v_lshlrev_b32_e32 v54, 16, v54
	v_lshlrev_b32_e32 v57, 16, v57
	v_lshlrev_b32_e32 v56, 16, v56
	v_lshlrev_b32_e32 v59, 16, v59
	v_lshlrev_b32_e32 v58, 16, v58
	v_lshlrev_b32_e32 v61, 16, v61
	v_lshlrev_b32_e32 v60, 16, v60
	v_lshlrev_b32_e32 v65, 16, v65
	v_lshlrev_b32_e32 v64, 16, v64
	v_lshlrev_b32_e32 v81, 16, v81
	v_lshlrev_b32_e32 v80, 16, v80
	v_lshlrev_b32_e32 v83, 16, v83
	v_lshlrev_b32_e32 v82, 16, v82
	v_lshlrev_b32_e32 v85, 16, v85
	v_lshlrev_b32_e32 v84, 16, v84
	v_lshlrev_b32_e32 v87, 16, v87
	v_lshlrev_b32_e32 v86, 16, v86
	v_lshlrev_b32_e32 v89, 16, v89
	v_lshlrev_b32_e32 v88, 16, v88
	v_lshlrev_b32_e32 v91, 16, v91
	v_lshlrev_b32_e32 v90, 16, v90
	v_lshlrev_b32_e32 v93, 16, v93
	v_lshlrev_b32_e32 v92, 16, v92
	v_pk_mul_f32 v[30:31], v[110:111], v[30:31]
	v_pk_mul_f32 v[32:33], v[112:113], v[32:33]
	v_pk_mul_f32 v[34:35], v[114:115], v[34:35]
	v_pk_mul_f32 v[36:37], v[116:117], v[36:37]
	v_pk_mul_f32 v[38:39], v[110:111], v[38:39]
	v_pk_mul_f32 v[40:41], v[112:113], v[40:41]
	v_pk_mul_f32 v[42:43], v[114:115], v[42:43]
	v_pk_mul_f32 v[44:45], v[116:117], v[44:45]
	v_pk_mul_f32 v[46:47], v[110:111], v[46:47]
	v_pk_mul_f32 v[48:49], v[112:113], v[48:49]
	v_pk_mul_f32 v[50:51], v[114:115], v[50:51]
	v_pk_mul_f32 v[52:53], v[116:117], v[52:53]
	v_pk_mul_f32 v[54:55], v[110:111], v[54:55]
	v_pk_mul_f32 v[56:57], v[112:113], v[56:57]
	v_pk_mul_f32 v[58:59], v[114:115], v[58:59]
	v_pk_mul_f32 v[60:61], v[116:117], v[60:61]
	v_pk_mul_f32 v[64:65], v[110:111], v[64:65]
	v_pk_mul_f32 v[80:81], v[112:113], v[80:81]
	v_pk_mul_f32 v[82:83], v[114:115], v[82:83]
	v_pk_mul_f32 v[84:85], v[116:117], v[84:85]
	v_pk_mul_f32 v[86:87], v[110:111], v[86:87]
	v_pk_mul_f32 v[88:89], v[112:113], v[88:89]
	v_pk_mul_f32 v[90:91], v[114:115], v[90:91]
	v_pk_mul_f32 v[92:93], v[116:117], v[92:93]
	v_pk_mul_f32 v[94:95], v[110:111], v[94:95]
	v_pk_mul_f32 v[96:97], v[112:113], v[96:97]
	v_pk_mul_f32 v[98:99], v[114:115], v[98:99]
	v_pk_mul_f32 v[100:101], v[116:117], v[100:101]
	v_pk_mul_f32 v[102:103], v[110:111], v[102:103]
	v_pk_mul_f32 v[104:105], v[112:113], v[104:105]
	v_pk_mul_f32 v[106:107], v[114:115], v[106:107]
	v_pk_mul_f32 v[108:109], v[116:117], v[108:109]
	v_cvt_pk_bf16_f32 v30, v30, v31
	v_cvt_pk_bf16_f32 v31, v32, v33
	v_cvt_pk_bf16_f32 v32, v34, v35
	v_cvt_pk_bf16_f32 v33, v36, v37
	v_cvt_pk_bf16_f32 v34, v38, v39
	v_cvt_pk_bf16_f32 v35, v40, v41
	v_cvt_pk_bf16_f32 v36, v42, v43
	v_cvt_pk_bf16_f32 v37, v44, v45
	v_cvt_pk_bf16_f32 v38, v46, v47
	v_cvt_pk_bf16_f32 v39, v48, v49
	v_cvt_pk_bf16_f32 v40, v50, v51
	v_cvt_pk_bf16_f32 v41, v52, v53
	v_cvt_pk_bf16_f32 v42, v54, v55
	v_cvt_pk_bf16_f32 v43, v56, v57
	v_cvt_pk_bf16_f32 v44, v58, v59
	v_cvt_pk_bf16_f32 v45, v60, v61
	v_cvt_pk_bf16_f32 v46, v64, v65
	v_cvt_pk_bf16_f32 v47, v80, v81
	v_cvt_pk_bf16_f32 v48, v82, v83
	v_cvt_pk_bf16_f32 v49, v84, v85
	v_cvt_pk_bf16_f32 v50, v86, v87
	v_cvt_pk_bf16_f32 v51, v88, v89
	v_cvt_pk_bf16_f32 v52, v90, v91
	v_cvt_pk_bf16_f32 v53, v92, v93
	v_cvt_pk_bf16_f32 v54, v94, v95
	v_cvt_pk_bf16_f32 v55, v96, v97
	v_cvt_pk_bf16_f32 v56, v98, v99
	v_cvt_pk_bf16_f32 v57, v100, v101
	v_cvt_pk_bf16_f32 v58, v102, v103
	v_cvt_pk_bf16_f32 v59, v104, v105
	v_cvt_pk_bf16_f32 v60, v106, v107
	v_cvt_pk_bf16_f32 v61, v108, v109
	global_store_dwordx4 v[66:67], v[30:33], off
	global_store_dwordx4 v[68:69], v[34:37], off
	global_store_dwordx4 v[70:71], v[38:41], off
	global_store_dwordx4 v[72:73], v[42:45], off
	global_store_dwordx4 v[74:75], v[46:49], off
	global_store_dwordx4 v[76:77], v[50:53], off
	global_store_dwordx4 v[78:79], v[54:57], off
	global_store_dwordx4 v[62:63], v[58:61], off
	s_waitcnt lgkmcnt(0)
	s_add_i32 s2, s2, s3
	s_add_i32 s8, s8, s9
	s_cmpk_lt_i32 s2, 0x2000
	s_cbranch_scc1 .LBB0_382

.LBB0_848:
	s_cmp_lt_i32 s4, 8
	s_cselect_b64 s[0:1], -1, 0
	s_cmp_gt_i32 s5, 7
	s_cselect_b64 s[2:3], -1, 0
	s_and_b64 s[0:1], s[0:1], s[2:3]
	s_andn2_b64 vcc, exec, s[0:1]
	s_cbranch_vccnz .LBB0_912
	v_readlane_b32 s0, v254, 15
	s_lshl_b32 s0, s0, 3
	s_add_i32 s6, s76, s0
	s_cmp_gt_i32 s6, 63
	v_readlane_b32 s1, v254, 16
	v_mbcnt_lo_u32_b32 v130, -1, 0
	v_mbcnt_hi_u32_b32 v130, -1, v130
	s_cbranch_scc1 .LBB0_851
	v_lshl_add_u32 v0, s6, 6, v130
	v_ashrrev_i32_e32 v1, 31, v0
	v_readlane_b32 s8, v254, 17
	v_lshlrev_b64 v[2:3], 2, v[0:1]
	v_readlane_b32 s9, v254, 18
	v_readlane_b32 s10, v254, 19
	v_readlane_b32 s11, v254, 20
	v_readlane_b32 s12, v254, 21
	v_readlane_b32 s13, v254, 22
	v_readlane_b32 s14, v254, 23
	v_readlane_b32 s15, v254, 24
	v_readlane_b32 s16, v254, 25
	v_readlane_b32 s17, v254, 26
	v_readlane_b32 s18, v254, 27
	v_readlane_b32 s19, v254, 28
	v_readlane_b32 s20, v254, 29
	v_readlane_b32 s21, v254, 30
	v_readlane_b32 s22, v254, 31
	v_readlane_b32 s23, v254, 32
	v_lshl_add_u64 v[0:1], v[0:1], 3, s[58:59]
	s_mov_b32 s0, 0x3f9837f0
	v_lshl_add_u64 v[4:5], s[22:23], 0, v[2:3]
	v_readlane_b32 s8, v254, 37
	v_readlane_b32 s9, v254, 38
	global_load_dword v4, v[4:5], off
	v_add_co_u32_e32 v0, vcc, 0x48020000, v0
	v_lshl_add_u64 v[2:3], s[8:9], 0, v[2:3]
	global_load_dword v5, v[2:3], off
	v_addc_co_u32_e32 v1, vcc, 0, v1, vcc
	v_readlane_b32 s10, v254, 39
	v_readlane_b32 s11, v254, 40
	v_readlane_b32 s12, v254, 41
	v_readlane_b32 s13, v254, 42
	v_readlane_b32 s14, v254, 43
	v_readlane_b32 s15, v254, 44
	v_readlane_b32 s16, v254, 45
	v_readlane_b32 s17, v254, 46
	v_readlane_b32 s18, v254, 47
	v_readlane_b32 s19, v254, 48
	v_readlane_b32 s20, v254, 49
	v_readlane_b32 s21, v254, 50
	v_readlane_b32 s22, v254, 51
	v_readlane_b32 s23, v254, 52
	s_waitcnt vmcnt(0)
	v_pk_mul_f32 v[2:3], v[4:5], s[0:1] op_sel_hi:[1,0]
	global_store_dwordx2 v[0:1], v[2:3], off nt
.LBB0_851:
	s_cmpk_gt_i32 s6, 0x3fff
	s_cbranch_scc1 .LBB0_856
	v_lshlrev_b32_e32 v56, 1, v130
	v_readlane_b32 s8, v254, 17
	v_ashrrev_i32_e32 v57, 31, v56
	v_readlane_b32 s14, v254, 23
	v_readlane_b32 s15, v254, 24
	v_readlane_b32 s22, v254, 31
	v_readlane_b32 s23, v254, 32
	v_lshlrev_b64 v[64:65], 4, v[56:57]
	s_mov_b64 s[14:15], s[22:23]
	v_lshl_add_u64 v[16:17], s[14:15], 0, v[64:65]
	global_load_dwordx4 v[0:3], v[16:17], off offset:16 nt
	global_load_dwordx4 v[4:7], v[16:17], off nt
	global_load_dwordx4 v[8:11], v[16:17], off offset:2064 nt
	global_load_dwordx4 v[12:15], v[16:17], off offset:2048 nt
	v_add_u32_e32 v16, 0x100, v56
	v_ashrrev_i32_e32 v17, 31, v16
	v_lshlrev_b64 v[80:81], 4, v[16:17]
	v_lshl_add_u64 v[24:25], s[14:15], 0, v[80:81]
	global_load_dwordx4 v[16:19], v[24:25], off offset:16 nt
	global_load_dwordx4 v[20:23], v[24:25], off nt
	v_add_u32_e32 v24, 0x180, v56
	v_ashrrev_i32_e32 v25, 31, v24
	v_lshlrev_b64 v[88:89], 4, v[24:25]
	v_lshl_add_u64 v[32:33], s[14:15], 0, v[88:89]
	global_load_dwordx4 v[24:27], v[32:33], off offset:16 nt
	global_load_dwordx4 v[28:31], v[32:33], off nt
	v_add_u32_e32 v32, 0x200, v56
	v_ashrrev_i32_e32 v33, 31, v32
	v_lshlrev_b64 v[96:97], 4, v[32:33]
	v_lshl_add_u64 v[40:41], s[14:15], 0, v[96:97]
	global_load_dwordx4 v[32:35], v[40:41], off offset:16 nt
	global_load_dwordx4 v[36:39], v[40:41], off nt
	v_add_u32_e32 v40, 0x280, v56
	v_ashrrev_i32_e32 v41, 31, v40
	v_lshlrev_b64 v[104:105], 4, v[40:41]
	v_lshl_add_u64 v[48:49], s[14:15], 0, v[104:105]
	global_load_dwordx4 v[40:43], v[48:49], off offset:16 nt
	global_load_dwordx4 v[44:47], v[48:49], off nt
	v_add_u32_e32 v48, 0x300, v56
	v_add_u32_e32 v56, 0x380, v56
	v_ashrrev_i32_e32 v49, 31, v48
	v_ashrrev_i32_e32 v57, 31, v56
	v_readlane_b32 s9, v254, 18
	v_readlane_b32 s10, v254, 19
	v_readlane_b32 s11, v254, 20
	v_readlane_b32 s12, v254, 21
	v_readlane_b32 s13, v254, 22
	v_readlane_b32 s16, v254, 25
	v_readlane_b32 s17, v254, 26
	v_readlane_b32 s18, v254, 27
	v_readlane_b32 s19, v254, 28
	v_readlane_b32 s20, v254, 29
	v_readlane_b32 s21, v254, 30
	v_lshlrev_b64 v[112:113], 4, v[48:49]
	v_lshlrev_b64 v[120:121], 4, v[56:57]
	v_lshl_add_u64 v[58:59], s[14:15], 0, v[112:113]
	v_lshl_add_u64 v[66:67], s[14:15], 0, v[120:121]
	v_readlane_b32 s8, v254, 37
	v_readlane_b32 s9, v254, 38
	s_mov_b64 s[0:1], s[8:9]
	v_lshl_add_u64 v[82:83], s[0:1], 0, v[64:65]
	global_load_dwordx4 v[48:51], v[58:59], off offset:16 nt
	global_load_dwordx4 v[52:55], v[58:59], off nt
	s_nop 0
	global_load_dwordx4 v[56:59], v[66:67], off offset:16 nt
	global_load_dwordx4 v[60:63], v[66:67], off nt
	s_nop 0
	global_load_dwordx4 v[64:67], v[82:83], off offset:16 nt
	global_load_dwordx4 v[68:71], v[82:83], off nt
	global_load_dwordx4 v[72:75], v[82:83], off offset:2064 nt
	global_load_dwordx4 v[76:79], v[82:83], off offset:2048 nt
	v_lshl_add_u64 v[90:91], s[0:1], 0, v[80:81]
	v_lshl_add_u64 v[98:99], s[0:1], 0, v[88:89]
	v_lshl_add_u64 v[106:107], s[0:1], 0, v[96:97]
	v_lshl_add_u64 v[114:115], s[0:1], 0, v[104:105]
	v_lshl_add_u64 v[122:123], s[0:1], 0, v[112:113]
	v_lshl_add_u64 v[124:125], s[0:1], 0, v[120:121]
	global_load_dwordx4 v[80:83], v[90:91], off offset:16 nt
	global_load_dwordx4 v[84:87], v[90:91], off nt
	s_nop 0
	global_load_dwordx4 v[88:91], v[98:99], off offset:16 nt
	global_load_dwordx4 v[92:95], v[98:99], off nt
	s_nop 0
	global_load_dwordx4 v[96:99], v[106:107], off offset:16 nt
	global_load_dwordx4 v[100:103], v[106:107], off nt
	s_nop 0
	global_load_dwordx4 v[104:107], v[114:115], off offset:16 nt
	global_load_dwordx4 v[108:111], v[114:115], off nt
	s_nop 0
	global_load_dwordx4 v[112:115], v[122:123], off offset:16 nt
	global_load_dwordx4 v[116:119], v[122:123], off nt
	s_nop 0
	global_load_dwordx4 v[120:123], v[124:125], off offset:16 nt
	s_nop 0
	global_load_dwordx4 v[124:127], v[124:125], off nt
	v_mbcnt_lo_u32_b32 v128, -1, 0
	v_mbcnt_hi_u32_b32 v128, -1, v128
	v_and_b32_e32 v129, 64, v128
	v_add_u32_e32 v129, 64, v129
	v_xor_b32_e32 v132, 1, v128
	v_cmp_lt_i32_e32 vcc, v132, v129
	v_readlane_b32 s0, v254, 6
	s_ashr_i32 s7, s6, 31
	v_cndmask_b32_e32 v132, v128, v132, vcc
	v_lshlrev_b32_e32 v208, 2, v132
	v_xor_b32_e32 v132, 2, v128
	v_cmp_lt_i32_e32 vcc, v132, v129
	s_lshl_b32 s8, s0, 3
	s_lshl_b64 s[2:3], s[6:7], 3
	v_cndmask_b32_e32 v132, v128, v132, vcc
	v_lshlrev_b32_e32 v209, 2, v132
	v_xor_b32_e32 v132, 4, v128
	v_cmp_lt_i32_e32 vcc, v132, v129
	s_add_u32 s2, s2, 0x48000000
	v_ashrrev_i32_e32 v131, 31, v130
	v_cndmask_b32_e32 v132, v128, v132, vcc
	v_lshlrev_b32_e32 v210, 2, v132
	v_xor_b32_e32 v132, 8, v128
	v_cmp_lt_i32_e32 vcc, v132, v129
	s_addc_u32 s3, s3, 0
	s_lshl_b64 s[4:5], s[6:7], 12
	v_cndmask_b32_e32 v132, v128, v132, vcc
	v_lshlrev_b32_e32 v211, 2, v132
	v_xor_b32_e32 v132, 16, v128
	v_cmp_lt_i32_e32 vcc, v132, v129
	v_readlane_b32 s10, v254, 39
	v_readlane_b32 s11, v254, 40
	v_cndmask_b32_e32 v132, v128, v132, vcc
	v_lshlrev_b32_e32 v212, 2, v132
	v_xor_b32_e32 v132, 32, v128
	v_cmp_lt_i32_e32 vcc, v132, v129
	v_readlane_b32 s12, v254, 41
	v_readlane_b32 s13, v254, 42
	v_cndmask_b32_e32 v128, v128, v132, vcc
	v_readlane_b32 s14, v254, 43
	v_readlane_b32 s15, v254, 44
	v_readlane_b32 s16, v254, 45
	v_readlane_b32 s17, v254, 46
	v_readlane_b32 s18, v254, 47
	v_readlane_b32 s1, v254, 7
	v_lshlrev_b32_e32 v213, 2, v128
	s_ashr_i32 s9, s8, 31
	v_lshl_add_u64 v[128:129], v[130:131], 3, s[4:5]
	s_lshl_b64 s[4:5], s[6:7], 13
	v_cmp_eq_u32_e64 s[0:1], 0, v130
	s_lshl_b64 s[10:11], s[8:9], 3
	s_lshl_b64 s[12:13], s[8:9], 12
	v_lshl_add_u64 v[130:131], v[130:131], 4, s[4:5]
	s_lshl_b64 s[14:15], s[8:9], 13
	v_mov_b32_e32 v132, 0
	s_mov_b32 s7, 0x2e001000
	v_mov_b32_e32 v214, 0x3727c5ac
	s_mov_b32 s9, 0xf800000
	v_mov_b32_e32 v215, 0x260
	s_brev_b32 s16, 26
	s_brev_b32 s17, 54
	s_mov_b32 s18, 0x58001000
	v_readlane_b32 s19, v254, 48
	v_readlane_b32 s20, v254, 49
	v_readlane_b32 s21, v254, 50
	v_readlane_b32 s22, v254, 51
	v_readlane_b32 s23, v254, 52
	s_branch .LBB0_854
.LBB0_853:
	s_or_b64 exec, exec, s[4:5]
	v_mov_b32_e32 v217, v194
	v_mov_b32_e32 v194, v203
	v_pk_mul_f32 v[194:195], v[194:195], v[138:139] op_sel_hi:[1,0]
	v_mov_b32_e32 v229, v132
	v_pk_fma_f32 v[224:225], v[0:1], v[194:195], v[64:65]
	v_mov_b32_e32 v216, v202
	v_cvt_pk_fp8_f32 v229, v224, v225
	v_mov_b32_e32 v223, v196
	v_mov_b32_e32 v196, v199
	v_mov_b32_e32 v218, v192
	v_mov_b32_e32 v219, v190
	v_mov_b32_e32 v220, v188
	v_mov_b32_e32 v221, v186
	v_pk_mul_f32 v[216:217], v[216:217], v[138:139] op_sel_hi:[1,0]
	v_pk_mul_f32 v[196:197], v[196:197], v[138:139] op_sel_hi:[1,0]
	v_mov_b32_e32 v222, v198
	v_pk_fma_f32 v[216:217], v[4:5], v[216:217], v[68:69]
	v_pk_fma_f32 v[198:199], v[2:3], v[196:197], v[66:67]
	v_mov_b32_e32 v228, v132
	v_mov_b32_e32 v190, v193
	v_pk_mul_f32 v[192:193], v[218:219], v[138:139] op_sel_hi:[1,0]
	v_mov_b32_e32 v186, v189
	v_pk_mul_f32 v[188:189], v[220:221], v[138:139] op_sel_hi:[1,0]
	v_cvt_pk_bf16_f32 v197, v198, v199
	v_add_co_u32_e32 v226, vcc, s16, v162
	v_cvt_pk_fp8_f32 v228, v216, v217
	v_cvt_pk_fp8_f32 v229, v198, v199 op_sel:[0,0,1]
	v_pk_fma_f32 v[192:193], v[12:13], v[192:193], v[76:77]
	v_pk_fma_f32 v[188:189], v[8:9], v[188:189], v[72:73]
	v_mov_b32_e32 v198, v132
	v_mov_b32_e32 v199, v132
	v_pk_mul_f32 v[222:223], v[222:223], v[138:139] op_sel_hi:[1,0]
	v_addc_co_u32_e32 v227, vcc, 0, v163, vcc
	v_cvt_pk_fp8_f32 v198, v192, v193
	v_cvt_pk_fp8_f32 v199, v188, v189
	v_pk_fma_f32 v[222:223], v[6:7], v[222:223], v[70:71]
	v_add_co_u32_e32 v162, vcc, s18, v162
	v_cvt_pk_bf16_f32 v194, v216, v217
	v_cvt_pk_bf16_f32 v195, v222, v223
	v_cvt_pk_bf16_f32 v196, v224, v225
	v_addc_co_u32_e32 v163, vcc, 0, v163, vcc
	v_pk_mul_f32 v[190:191], v[190:191], v[138:139] op_sel_hi:[1,0]
	v_pk_mul_f32 v[186:187], v[186:187], v[138:139] op_sel_hi:[1,0]
	global_store_dwordx4 v[162:163], v[194:197], off offset:-4096
	v_cvt_pk_fp8_f32 v228, v222, v223 op_sel:[0,0,1]
	v_pk_fma_f32 v[190:191], v[14:15], v[190:191], v[78:79]
	v_pk_fma_f32 v[196:197], v[10:11], v[186:187], v[74:75]
	v_mov_b32_e32 v134, v207
	v_lshl_add_u64 v[206:207], s[58:59], 0, v[128:129]
	v_cvt_pk_fp8_f32 v198, v190, v191 op_sel:[0,0,1]
	v_cvt_pk_fp8_f32 v199, v196, v197 op_sel:[0,0,1]
	v_add_co_u32_e32 v194, vcc, s17, v206
	v_cvt_pk_bf16_f32 v186, v192, v193
	s_nop 0
	v_addc_co_u32_e32 v195, vcc, 0, v207, vcc
	v_cvt_pk_bf16_f32 v187, v190, v191
	v_cvt_pk_bf16_f32 v188, v188, v189
	v_cvt_pk_bf16_f32 v189, v196, v197
	v_pk_mul_f32 v[182:183], v[182:183], v[138:139] op_sel_hi:[1,0]
	v_pk_mul_f32 v[180:181], v[180:181], v[138:139] op_sel_hi:[1,0]
	v_pk_mul_f32 v[178:179], v[178:179], v[138:139] op_sel_hi:[1,0]
	global_store_dwordx2 v[194:195], v[228:229], off nt
	global_store_dwordx4 v[226:227], v[186:189], off offset:1024
	global_store_dwordx2 v[194:195], v[198:199], off offset:512 nt
	v_pk_fma_f32 v[182:183], v[20:21], v[182:183], v[84:85]
	v_pk_fma_f32 v[186:187], v[18:19], v[180:181], v[82:83]
	v_pk_fma_f32 v[180:181], v[16:17], v[178:179], v[80:81]
	v_mov_b32_e32 v188, v132
	v_mov_b32_e32 v189, v132
	v_cvt_pk_fp8_f32 v188, v182, v183
	v_cvt_pk_fp8_f32 v189, v180, v181
	v_pk_mul_f32 v[184:185], v[184:185], v[138:139] op_sel_hi:[1,0]
	v_mov_b32_e32 v175, v133
	v_pk_fma_f32 v[184:185], v[22:23], v[184:185], v[86:87]
	v_cvt_pk_fp8_f32 v189, v186, v187 op_sel:[0,0,1]
	v_cvt_pk_fp8_f32 v188, v184, v185 op_sel:[0,0,1]
	v_mov_b32_e32 v168, v205
	v_mov_b32_e32 v170, v173
	v_cvt_pk_bf16_f32 v178, v182, v183
	v_cvt_pk_bf16_f32 v179, v184, v185
	v_cvt_pk_bf16_f32 v180, v180, v181
	v_cvt_pk_bf16_f32 v181, v186, v187
	v_pk_mul_f32 v[174:175], v[174:175], v[138:139] op_sel_hi:[1,0]
	v_pk_mul_f32 v[170:171], v[170:171], v[138:139] op_sel_hi:[1,0]
	v_pk_mul_f32 v[168:169], v[168:169], v[138:139] op_sel_hi:[1,0]
	global_store_dwordx4 v[226:227], v[178:181], off offset:2048
	global_store_dwordx2 v[194:195], v[188:189], off offset:1024 nt
	v_pk_fma_f32 v[174:175], v[28:29], v[174:175], v[92:93]
	v_pk_fma_f32 v[172:173], v[26:27], v[170:171], v[90:91]
	v_pk_fma_f32 v[170:171], v[24:25], v[168:169], v[88:89]
	v_mov_b32_e32 v178, v132
	v_mov_b32_e32 v179, v132
	v_cvt_pk_fp8_f32 v178, v174, v175
	v_cvt_pk_fp8_f32 v179, v170, v171
	v_pk_mul_f32 v[176:177], v[176:177], v[138:139] op_sel_hi:[1,0]
	v_mov_b32_e32 v204, v200
	v_pk_fma_f32 v[176:177], v[30:31], v[176:177], v[94:95]
	v_cvt_pk_fp8_f32 v179, v172, v173 op_sel:[0,0,1]
	v_cvt_pk_fp8_f32 v178, v176, v177 op_sel:[0,0,1]
	v_mov_b32_e32 v205, v160
	v_mov_b32_e32 v160, v201
	v_cvt_pk_bf16_f32 v168, v174, v175
	v_cvt_pk_bf16_f32 v169, v176, v177
	v_cvt_pk_bf16_f32 v170, v170, v171
	v_cvt_pk_bf16_f32 v171, v172, v173
	global_store_dwordx4 v[226:227], v[168:171], off offset:3072
	global_store_dwordx2 v[194:195], v[178:179], off offset:1536 nt
	v_pk_mul_f32 v[160:161], v[160:161], v[138:139] op_sel_hi:[1,0]
	v_pk_mul_f32 v[170:171], v[204:205], v[138:139] op_sel_hi:[1,0]
	v_pk_fma_f32 v[160:161], v[32:33], v[160:161], v[96:97]
	v_pk_fma_f32 v[170:171], v[36:37], v[170:171], v[100:101]
	v_mov_b32_e32 v174, v132
	v_mov_b32_e32 v175, v132
	v_cvt_pk_fp8_f32 v174, v170, v171
	v_cvt_pk_fp8_f32 v175, v160, v161
	v_mov_b32_e32 v168, v166
	v_mov_b32_e32 v169, v164
	v_mov_b32_e32 v164, v167
	v_pk_mul_f32 v[168:169], v[168:169], v[138:139] op_sel_hi:[1,0]
	v_pk_mul_f32 v[164:165], v[164:165], v[138:139] op_sel_hi:[1,0]
	v_pk_fma_f32 v[168:169], v[38:39], v[168:169], v[102:103]
	v_pk_fma_f32 v[172:173], v[34:35], v[164:165], v[98:99]
	v_cvt_pk_fp8_f32 v174, v168, v169 op_sel:[0,0,1]
	v_cvt_pk_fp8_f32 v175, v172, v173 op_sel:[0,0,1]
	v_mov_b32_e32 v202, v150
	v_mov_b32_e32 v203, v148
	v_mov_b32_e32 v200, v146
	v_mov_b32_e32 v201, v144
	v_cvt_pk_bf16_f32 v164, v170, v171
	v_cvt_pk_bf16_f32 v165, v168, v169
	v_cvt_pk_bf16_f32 v166, v160, v161
	v_cvt_pk_bf16_f32 v167, v172, v173
	v_mov_b32_e32 v148, v151
	v_pk_mul_f32 v[150:151], v[202:203], v[138:139] op_sel_hi:[1,0]
	v_mov_b32_e32 v144, v147
	v_pk_mul_f32 v[146:147], v[200:201], v[138:139] op_sel_hi:[1,0]
	global_store_dwordx4 v[162:163], v[164:167], off
	global_store_dwordx2 v[194:195], v[174:175], off offset:2048 nt
	v_pk_fma_f32 v[150:151], v[44:45], v[150:151], v[108:109]
	v_pk_fma_f32 v[146:147], v[40:41], v[146:147], v[104:105]
	v_mov_b32_e32 v164, v132
	v_mov_b32_e32 v165, v132
	v_cvt_pk_fp8_f32 v164, v150, v151
	v_cvt_pk_fp8_f32 v165, v146, v147
	v_pk_mul_f32 v[148:149], v[148:149], v[138:139] op_sel_hi:[1,0]
	v_pk_mul_f32 v[144:145], v[144:145], v[138:139] op_sel_hi:[1,0]
	v_pk_fma_f32 v[148:149], v[46:47], v[148:149], v[110:111]
	v_pk_fma_f32 v[160:161], v[42:43], v[144:145], v[106:107]
	v_cvt_pk_fp8_f32 v164, v148, v149 op_sel:[0,0,1]
	v_cvt_pk_fp8_f32 v165, v160, v161 op_sel:[0,0,1]
	v_cvt_pk_bf16_f32 v144, v150, v151
	v_cvt_pk_bf16_f32 v145, v148, v149
	v_cvt_pk_bf16_f32 v146, v146, v147
	v_cvt_pk_bf16_f32 v147, v160, v161
	global_store_dwordx4 v[162:163], v[144:147], off offset:1024
	global_store_dwordx2 v[194:195], v[164:165], off offset:2560 nt
	v_pk_mul_f32 v[150:151], v[152:153], v[138:139] op_sel_hi:[1,0]
	v_pk_mul_f32 v[144:145], v[158:159], v[138:139] op_sel_hi:[1,0]
	v_pk_mul_f32 v[146:147], v[156:157], v[138:139] op_sel_hi:[1,0]
	v_pk_fma_f32 v[148:149], v[54:55], v[144:145], v[118:119]
	v_pk_fma_f32 v[144:145], v[52:53], v[146:147], v[116:117]
	v_pk_mul_f32 v[146:147], v[154:155], v[138:139] op_sel_hi:[1,0]
	v_mov_b32_e32 v136, v139
	v_pk_fma_f32 v[152:153], v[50:51], v[146:147], v[114:115]
	v_pk_fma_f32 v[146:147], v[48:49], v[150:151], v[112:113]
	v_mov_b32_e32 v150, v132
	v_mov_b32_e32 v151, v132
	v_cvt_pk_fp8_f32 v150, v144, v145
	v_cvt_pk_fp8_f32 v151, v146, v147
	v_cvt_pk_bf16_f32 v144, v144, v145
	v_cvt_pk_bf16_f32 v145, v148, v149
	v_cvt_pk_fp8_f32 v150, v148, v149 op_sel:[0,0,1]
	v_cvt_pk_fp8_f32 v151, v152, v153 op_sel:[0,0,1]
	v_cvt_pk_bf16_f32 v146, v146, v147
	v_cvt_pk_bf16_f32 v147, v152, v153
	v_pk_mul_f32 v[140:141], v[140:141], v[138:139] op_sel_hi:[1,0]
	v_pk_mul_f32 v[136:137], v[136:137], v[138:139] op_sel_hi:[1,0]
	v_pk_mul_f32 v[134:135], v[134:135], v[138:139] op_sel_hi:[1,0]
	global_store_dwordx4 v[162:163], v[144:147], off offset:2048
	global_store_dwordx2 v[194:195], v[150:151], off offset:3072 nt
	v_pk_mul_f32 v[142:143], v[142:143], v[138:139] op_sel_hi:[1,0]
	v_pk_fma_f32 v[140:141], v[60:61], v[140:141], v[124:125]
	v_pk_fma_f32 v[138:139], v[58:59], v[136:137], v[122:123]
	v_pk_fma_f32 v[136:137], v[56:57], v[134:135], v[120:121]
	v_mov_b32_e32 v144, v132
	v_mov_b32_e32 v145, v132
	v_cvt_pk_fp8_f32 v144, v140, v141
	v_cvt_pk_fp8_f32 v145, v136, v137
	v_pk_fma_f32 v[142:143], v[62:63], v[142:143], v[126:127]
	s_add_i32 s6, s6, s8
	v_cvt_pk_fp8_f32 v144, v142, v143 op_sel:[0,0,1]
	v_cvt_pk_fp8_f32 v145, v138, v139 op_sel:[0,0,1]
	s_add_u32 s2, s2, s10
	s_addc_u32 s3, s3, s11
	v_cvt_pk_bf16_f32 v134, v140, v141
	v_cvt_pk_bf16_f32 v135, v142, v143
	v_cvt_pk_bf16_f32 v136, v136, v137
	v_cvt_pk_bf16_f32 v137, v138, v139
	v_lshl_add_u64 v[128:129], v[128:129], 0, s[12:13]
	s_cmpk_lt_i32 s6, 0x4000
	v_lshl_add_u64 v[130:131], v[130:131], 0, s[14:15]
	global_store_dwordx4 v[162:163], v[134:137], off offset:3072
	global_store_dwordx2 v[194:195], v[144:145], off offset:3584 nt
	s_cbranch_scc0 .LBB0_856
.LBB0_854:
	v_lshl_add_u64 v[162:163], s[58:59], 0, v[130:131]
	v_add_co_u32_e32 v142, vcc, s7, v162
	s_nop 1
	v_addc_co_u32_e32 v143, vcc, 0, v163, vcc
	global_load_dwordx4 v[134:137], v[142:143], off nt
	global_load_dwordx4 v[138:141], v[142:143], off offset:1024 nt
	v_add_co_u32_e32 v144, vcc, 0x2e000000, v162
	s_waitcnt vmcnt(1)
	v_lshlrev_b32_e32 v201, 16, v136
	v_addc_co_u32_e32 v145, vcc, 0, v163, vcc
	global_load_dwordx4 v[152:155], v[144:145], off nt
	global_load_dwordx4 v[156:159], v[144:145], off offset:1024 nt
	global_load_dwordx4 v[168:171], v[144:145], off offset:2048 nt
	global_load_dwordx4 v[204:207], v[144:145], off offset:3072 nt
	global_load_dwordx4 v[216:219], v[142:143], off offset:2048 nt
	global_load_dwordx4 v[220:223], v[142:143], off offset:3072 nt
	v_lshlrev_b32_e32 v200, 16, v134
	v_and_b32_e32 v161, 0xffff0000, v136
	v_and_b32_e32 v160, 0xffff0000, v134
	v_lshlrev_b32_e32 v167, 16, v137
	v_lshlrev_b32_e32 v166, 16, v135
	v_and_b32_e32 v165, 0xffff0000, v137
	v_and_b32_e32 v164, 0xffff0000, v135
	s_waitcnt vmcnt(6)
	v_lshlrev_b32_e32 v151, 16, v139
	v_lshlrev_b32_e32 v150, 16, v138
	v_and_b32_e32 v149, 0xffff0000, v139
	v_and_b32_e32 v148, 0xffff0000, v138
	v_pk_add_f32 v[134:135], v[200:201], v[160:161]
	v_pk_add_f32 v[136:137], v[166:167], v[164:165]
	v_lshlrev_b32_e32 v147, 16, v141
	v_pk_add_f32 v[226:227], v[134:135], v[136:137]
	v_lshlrev_b32_e32 v146, 16, v140
	v_and_b32_e32 v145, 0xffff0000, v141
	v_and_b32_e32 v144, 0xffff0000, v140
	v_pk_add_f32 v[224:225], v[150:151], v[148:149]
	v_pk_add_f32 v[230:231], v[146:147], v[144:145]
	s_waitcnt vmcnt(5)
	v_lshlrev_b32_e32 v203, 16, v154
	v_lshlrev_b32_e32 v202, 16, v152
	v_and_b32_e32 v195, 0xffff0000, v154
	v_and_b32_e32 v194, 0xffff0000, v152
	v_lshlrev_b32_e32 v199, 16, v155
	v_lshlrev_b32_e32 v198, 16, v153
	v_and_b32_e32 v197, 0xffff0000, v155
	v_and_b32_e32 v196, 0xffff0000, v153
	s_waitcnt vmcnt(4)
	v_lshlrev_b32_e32 v193, 16, v157
	v_lshlrev_b32_e32 v192, 16, v156
	v_and_b32_e32 v191, 0xffff0000, v157
	v_and_b32_e32 v190, 0xffff0000, v156
	v_lshlrev_b32_e32 v189, 16, v159
	v_lshlrev_b32_e32 v188, 16, v158
	v_and_b32_e32 v187, 0xffff0000, v159
	v_and_b32_e32 v186, 0xffff0000, v158
	v_pk_add_f32 v[138:139], v[202:203], v[194:195]
	v_pk_add_f32 v[142:143], v[198:199], v[196:197]
	v_pk_add_f32 v[152:153], v[192:193], v[190:191]
	v_pk_add_f32 v[154:155], v[188:189], v[186:187]
	v_pk_add_f32 v[134:135], v[138:139], v[142:143]
	s_waitcnt vmcnt(3)
	v_lshlrev_b32_e32 v182, 16, v168
	v_and_b32_e32 v183, 0xffff0000, v168
	v_lshlrev_b32_e32 v184, 16, v169
	v_and_b32_e32 v185, 0xffff0000, v169
	v_lshlrev_b32_e32 v178, 16, v170
	v_and_b32_e32 v179, 0xffff0000, v170
	v_lshlrev_b32_e32 v180, 16, v171
	v_and_b32_e32 v181, 0xffff0000, v171
	s_waitcnt vmcnt(2)
	v_lshlrev_b32_e32 v174, 16, v204
	v_lshlrev_b32_e32 v176, 16, v205
	v_and_b32_e32 v177, 0xffff0000, v205
	v_pk_add_f32 v[136:137], v[152:153], v[152:153] op_sel:[0,1] op_sel_hi:[1,0]
	v_pk_add_f32 v[138:139], v[154:155], v[154:155] op_sel:[0,1] op_sel_hi:[1,0]
	v_pk_add_f32 v[134:135], v[134:135], v[134:135] op_sel:[0,1] op_sel_hi:[1,0]
	v_and_b32_e32 v133, 0xffff0000, v204
	v_lshlrev_b32_e32 v205, 16, v206
	v_and_b32_e32 v169, 0xffff0000, v206
	v_lshlrev_b32_e32 v173, 16, v207
	v_and_b32_e32 v171, 0xffff0000, v207
	v_add_f32_e32 v204, v182, v183
	v_add_f32_e32 v168, v184, v185
	v_add_f32_e32 v172, v178, v179
	v_add_f32_e32 v170, v180, v181
	v_mov_b32_e32 v137, v176
	v_mov_b32_e32 v139, v177
	v_mov_b32_e32 v135, v174
	v_pk_add_f32 v[142:143], v[204:205], v[168:169]
	v_pk_add_f32 v[152:153], v[172:173], v[170:171]
	v_pk_add_f32 v[136:137], v[136:137], v[138:139]
	v_pk_add_f32 v[134:135], v[134:135], v[132:133]
	v_pk_add_f32 v[142:143], v[142:143], v[152:153]
	v_pk_add_f32 v[134:135], v[134:135], v[136:137]
	s_waitcnt vmcnt(1)
	v_lshlrev_b32_e32 v156, 16, v216
	v_pk_add_f32 v[228:229], v[134:135], v[142:143]
	v_and_b32_e32 v157, 0xffff0000, v216
	v_lshlrev_b32_e32 v158, 16, v217
	v_and_b32_e32 v159, 0xffff0000, v217
	v_lshlrev_b32_e32 v152, 16, v218
	v_and_b32_e32 v153, 0xffff0000, v218
	v_lshlrev_b32_e32 v154, 16, v219
	v_and_b32_e32 v155, 0xffff0000, v219
	s_waitcnt vmcnt(0)
	v_lshlrev_b32_e32 v140, 16, v220
	v_and_b32_e32 v141, 0xffff0000, v220
	v_pk_add_f32 v[216:217], v[228:229], v[228:229] op_sel:[0,1] op_sel_hi:[1,0]
	v_pk_add_f32 v[218:219], v[226:227], v[226:227] op_sel:[0,1] op_sel_hi:[1,0]
	v_mov_b32_e32 v217, v140
	v_mov_b32_e32 v219, v141
	v_lshlrev_b32_e32 v142, 16, v221
	v_and_b32_e32 v143, 0xffff0000, v221
	v_pk_add_f32 v[216:217], v[216:217], v[218:219]
	v_pk_add_f32 v[218:219], v[224:225], v[224:225] op_sel:[0,1] op_sel_hi:[1,0]
	v_pk_add_f32 v[220:221], v[230:231], v[230:231] op_sel:[0,1] op_sel_hi:[1,0]
	v_mov_b32_e32 v219, v142
	v_mov_b32_e32 v221, v143
	v_add_f32_e32 v206, v156, v157
	v_add_f32_e32 v134, v158, v159
	v_add_f32_e32 v138, v152, v153
	v_add_f32_e32 v136, v154, v155
	v_lshlrev_b32_e32 v207, 16, v222
	v_and_b32_e32 v135, 0xffff0000, v222
	v_lshlrev_b32_e32 v139, 16, v223
	v_and_b32_e32 v137, 0xffff0000, v223
	v_pk_add_f32 v[218:219], v[218:219], v[220:221]
	v_pk_add_f32 v[220:221], v[138:139], v[136:137]
	v_pk_add_f32 v[216:217], v[216:217], v[218:219]
	v_pk_add_f32 v[218:219], v[206:207], v[134:135]
	s_nop 0
	v_pk_add_f32 v[218:219], v[218:219], v[220:221]
	s_nop 0
	v_pk_add_f32 v[216:217], v[216:217], v[218:219]
	s_nop 0
	v_add_f32_e32 v134, v216, v217
	ds_bpermute_b32 v136, v208, v134
	s_waitcnt lgkmcnt(0)
	v_add_f32_e32 v134, v134, v136
	ds_bpermute_b32 v136, v209, v134
	s_waitcnt lgkmcnt(0)
	v_add_f32_e32 v134, v134, v136
	ds_bpermute_b32 v136, v210, v134
	s_waitcnt lgkmcnt(0)
	v_add_f32_e32 v134, v134, v136
	ds_bpermute_b32 v136, v211, v134
	s_waitcnt lgkmcnt(0)
	v_add_f32_e32 v134, v134, v136
	ds_bpermute_b32 v136, v212, v134
	s_waitcnt lgkmcnt(0)
	v_add_f32_e32 v134, v134, v136
	ds_bpermute_b32 v136, v213, v134
	s_waitcnt lgkmcnt(0)
	v_add_f32_e32 v134, v134, v136
	v_fmac_f32_e32 v196, 0xb9800000, v134
	v_fmac_f32_e32 v194, 0xb9800000, v134
	v_fmac_f32_e32 v198, 0xb9800000, v134
	v_fmac_f32_e32 v202, 0xb9800000, v134
	v_mul_f32_e32 v136, v194, v194
	v_mul_f32_e32 v138, v196, v196
	v_fmac_f32_e32 v136, v202, v202
	v_fmac_f32_e32 v138, v198, v198
	v_fmac_f32_e32 v197, 0xb9800000, v134
	v_fmac_f32_e32 v195, 0xb9800000, v134
	v_add_f32_e32 v136, v136, v138
	v_fmac_f32_e32 v199, 0xb9800000, v134
	v_fmac_f32_e32 v203, 0xb9800000, v134
	v_mul_f32_e32 v138, v195, v195
	v_mul_f32_e32 v168, v197, v197
	v_fmac_f32_e32 v138, v203, v203
	v_fmac_f32_e32 v168, v199, v199
	v_add_f32_e32 v138, v138, v168
	v_fmac_f32_e32 v191, 0xb9800000, v134
	v_fmac_f32_e32 v190, 0xb9800000, v134
	v_add_f32_e32 v136, v136, v138
	v_fmac_f32_e32 v193, 0xb9800000, v134
	v_fmac_f32_e32 v192, 0xb9800000, v134
	v_mul_f32_e32 v138, v190, v190
	v_mul_f32_e32 v168, v191, v191
	v_fmac_f32_e32 v138, v192, v192
	v_fmac_f32_e32 v168, v193, v193
	v_add_f32_e32 v138, v138, v168
	v_fmac_f32_e32 v187, 0xb9800000, v134
	v_fmac_f32_e32 v186, 0xb9800000, v134
	v_add_f32_e32 v136, v138, v136
	v_fmac_f32_e32 v189, 0xb9800000, v134
	v_fmac_f32_e32 v188, 0xb9800000, v134
	v_mul_f32_e32 v138, v186, v186
	v_mul_f32_e32 v168, v187, v187
	v_fmac_f32_e32 v138, v188, v188
	v_fmac_f32_e32 v168, v189, v189
	v_add_f32_e32 v138, v138, v168
	v_fmac_f32_e32 v185, 0xb9800000, v134
	v_fmac_f32_e32 v183, 0xb9800000, v134
	v_add_f32_e32 v136, v138, v136
	v_fmac_f32_e32 v184, 0xb9800000, v134
	v_fmac_f32_e32 v182, 0xb9800000, v134
	v_mul_f32_e32 v138, v183, v183
	v_mul_f32_e32 v168, v185, v185
	v_fmac_f32_e32 v138, v182, v182
	v_fmac_f32_e32 v168, v184, v184
	v_add_f32_e32 v138, v138, v168
	v_fmac_f32_e32 v181, 0xb9800000, v134
	v_fmac_f32_e32 v179, 0xb9800000, v134
	v_add_f32_e32 v136, v138, v136
	v_fmac_f32_e32 v180, 0xb9800000, v134
	v_fmac_f32_e32 v178, 0xb9800000, v134
	v_mul_f32_e32 v138, v179, v179
	v_mul_f32_e32 v168, v181, v181
	v_fmac_f32_e32 v138, v178, v178
	v_fmac_f32_e32 v168, v180, v180
	v_add_f32_e32 v138, v138, v168
	v_fmac_f32_e32 v177, 0xb9800000, v134
	v_fmac_f32_e32 v133, 0xb9800000, v134
	v_add_f32_e32 v136, v138, v136
	v_fmac_f32_e32 v176, 0xb9800000, v134
	v_fmac_f32_e32 v174, 0xb9800000, v134
	v_mul_f32_e32 v138, v133, v133
	v_mul_f32_e32 v168, v177, v177
	v_fmac_f32_e32 v138, v174, v174
	v_fmac_f32_e32 v168, v176, v176
	v_add_f32_e32 v138, v138, v168
	v_fmac_f32_e32 v171, 0xb9800000, v134
	v_fmac_f32_e32 v169, 0xb9800000, v134
	v_add_f32_e32 v136, v138, v136
	v_fmac_f32_e32 v173, 0xb9800000, v134
	v_fmac_f32_e32 v205, 0xb9800000, v134
	v_mul_f32_e32 v138, v169, v169
	v_mul_f32_e32 v168, v171, v171
	v_fmac_f32_e32 v138, v205, v205
	v_fmac_f32_e32 v168, v173, v173
	v_add_f32_e32 v138, v138, v168
	v_fmac_f32_e32 v164, 0xb9800000, v134
	v_fmac_f32_e32 v160, 0xb9800000, v134
	v_add_f32_e32 v136, v138, v136
	v_fmac_f32_e32 v166, 0xb9800000, v134
	v_fmac_f32_e32 v200, 0xb9800000, v134
	v_mul_f32_e32 v138, v160, v160
	v_mul_f32_e32 v168, v164, v164
	v_fmac_f32_e32 v138, v200, v200
	v_fmac_f32_e32 v168, v166, v166
	v_add_f32_e32 v138, v138, v168
	v_fmac_f32_e32 v165, 0xb9800000, v134
	v_fmac_f32_e32 v161, 0xb9800000, v134
	v_add_f32_e32 v136, v138, v136
	v_fmac_f32_e32 v167, 0xb9800000, v134
	v_fmac_f32_e32 v201, 0xb9800000, v134
	v_mul_f32_e32 v138, v161, v161
	v_mul_f32_e32 v168, v165, v165
	v_fmac_f32_e32 v138, v201, v201
	v_fmac_f32_e32 v168, v167, v167
	v_add_f32_e32 v138, v138, v168
	v_fmac_f32_e32 v149, 0xb9800000, v134
	v_fmac_f32_e32 v148, 0xb9800000, v134
	v_add_f32_e32 v136, v138, v136
	v_fmac_f32_e32 v151, 0xb9800000, v134
	v_fmac_f32_e32 v150, 0xb9800000, v134
	v_mul_f32_e32 v138, v148, v148
	v_mul_f32_e32 v168, v149, v149
	v_fmac_f32_e32 v138, v150, v150
	v_fmac_f32_e32 v168, v151, v151
	v_add_f32_e32 v138, v138, v168
	v_fmac_f32_e32 v145, 0xb9800000, v134
	v_fmac_f32_e32 v144, 0xb9800000, v134
	v_add_f32_e32 v136, v138, v136
	v_fmac_f32_e32 v147, 0xb9800000, v134
	v_fmac_f32_e32 v146, 0xb9800000, v134
	v_mul_f32_e32 v138, v144, v144
	v_mul_f32_e32 v168, v145, v145
	v_fmac_f32_e32 v138, v146, v146
	v_fmac_f32_e32 v168, v147, v147
	v_add_f32_e32 v138, v138, v168
	v_fmac_f32_e32 v159, 0xb9800000, v134
	v_fmac_f32_e32 v157, 0xb9800000, v134
	v_add_f32_e32 v136, v138, v136
	v_fmac_f32_e32 v158, 0xb9800000, v134
	v_fmac_f32_e32 v156, 0xb9800000, v134
	v_mul_f32_e32 v138, v157, v157
	v_mul_f32_e32 v168, v159, v159
	v_fmac_f32_e32 v138, v156, v156
	v_fmac_f32_e32 v168, v158, v158
	v_add_f32_e32 v138, v138, v168
	v_fmac_f32_e32 v155, 0xb9800000, v134
	v_fmac_f32_e32 v153, 0xb9800000, v134
	v_add_f32_e32 v136, v138, v136
	v_fmac_f32_e32 v154, 0xb9800000, v134
	v_fmac_f32_e32 v152, 0xb9800000, v134
	v_mul_f32_e32 v138, v153, v153
	v_mul_f32_e32 v168, v155, v155
	v_fmac_f32_e32 v138, v152, v152
	v_fmac_f32_e32 v168, v154, v154
	v_add_f32_e32 v138, v138, v168
	v_fmac_f32_e32 v143, 0xb9800000, v134
	v_fmac_f32_e32 v141, 0xb9800000, v134
	v_add_f32_e32 v136, v138, v136
	v_fmac_f32_e32 v142, 0xb9800000, v134
	v_fmac_f32_e32 v140, 0xb9800000, v134
	v_mul_f32_e32 v138, v141, v141
	v_mul_f32_e32 v168, v143, v143
	v_fmac_f32_e32 v138, v140, v140
	v_fmac_f32_e32 v168, v142, v142
	v_add_f32_e32 v138, v138, v168
	v_fmac_f32_e32 v137, 0xb9800000, v134
	v_fmac_f32_e32 v135, 0xb9800000, v134
	v_add_f32_e32 v136, v138, v136
	v_fmac_f32_e32 v139, 0xb9800000, v134
	v_fmac_f32_e32 v207, 0xb9800000, v134
	v_mul_f32_e32 v138, v135, v135
	v_mul_f32_e32 v168, v137, v137
	v_fmac_f32_e32 v138, v207, v207
	v_fmac_f32_e32 v168, v139, v139
	v_add_f32_e32 v138, v138, v168
	v_add_f32_e32 v136, v138, v136
	ds_bpermute_b32 v138, v208, v136
	s_waitcnt lgkmcnt(0)
	v_add_f32_e32 v136, v136, v138
	ds_bpermute_b32 v138, v209, v136
	s_waitcnt lgkmcnt(0)
	v_add_f32_e32 v136, v136, v138
	ds_bpermute_b32 v138, v210, v136
	s_waitcnt lgkmcnt(0)
	v_add_f32_e32 v136, v136, v138
	ds_bpermute_b32 v138, v211, v136
	s_waitcnt lgkmcnt(0)
	v_add_f32_e32 v136, v136, v138
	ds_bpermute_b32 v138, v212, v136
	s_waitcnt lgkmcnt(0)
	v_add_f32_e32 v136, v136, v138
	ds_bpermute_b32 v138, v213, v136
	s_waitcnt lgkmcnt(0)
	v_add_f32_e32 v136, v136, v138
	v_fmamk_f32 v136, v136, 0x39800000, v214
	v_mul_f32_e32 v138, 0x4f800000, v136
	v_cmp_gt_f32_e32 vcc, s9, v136
	s_nop 1
	v_cndmask_b32_e32 v136, v136, v138, vcc
	v_sqrt_f32_e32 v138, v136
	s_nop 0
	v_add_u32_e32 v168, -1, v138
	v_fma_f32 v170, -v168, v138, v136
	v_cmp_ge_f32_e64 s[4:5], 0, v170
	v_add_u32_e32 v170, 1, v138
	s_nop 0
	v_cndmask_b32_e64 v168, v138, v168, s[4:5]
	v_fma_f32 v138, -v170, v138, v136
	v_cmp_lt_f32_e64 s[4:5], 0, v138
	s_nop 1
	v_cndmask_b32_e64 v138, v168, v170, s[4:5]
	v_mul_f32_e32 v168, 0x37800000, v138
	v_cndmask_b32_e32 v138, v138, v168, vcc
	v_cmp_class_f32_e32 vcc, v136, v215
	s_nop 1
	v_cndmask_b32_e32 v136, v138, v136, vcc
	v_div_scale_f32 v138, s[4:5], v136, v136, 1.0
	v_rcp_f32_e32 v168, v138
	s_nop 0
	v_fma_f32 v170, -v138, v168, 1.0
	v_fmac_f32_e32 v168, v170, v168
	v_div_scale_f32 v170, vcc, 1.0, v136, 1.0
	v_mul_f32_e32 v172, v170, v168
	v_fma_f32 v175, -v138, v172, v170
	v_fmac_f32_e32 v172, v175, v168
	v_fma_f32 v138, -v138, v172, v170
	v_div_fmas_f32 v138, v138, v168, v172
	v_div_fixup_f32 v138, v138, v136, 1.0
	s_and_saveexec_b64 s[4:5], s[0:1]
	s_cbranch_execz .LBB0_853
	s_add_u32 s20, s58, s2
	v_mul_f32_e32 v216, 0x39800000, v134
	s_addc_u32 s21, s59, s3
	v_mov_b32_e32 v217, v138
	global_store_dwordx2 v132, v[216:217], s[20:21]
	s_branch .LBB0_853
